# step 1: the 72 adaLN-GEMM workgroups convert 192 of layer 0's weight tiles after their GEMM tile (converters stop at 6 trips)
# speedup vs baseline: 1.0072x; 1.0072x over previous
; __device__ __forceinline__ void convert_layer(PP P, int l, LAS unsigned char* lds, const Ids I) {
;     ...
;     for (int u = BID; u < 7 * 176 + 64; u += NB) {
;         const int mi = u / 176, uu = u - mi * 176;
;         if (mi == 0)      conv_tile4(P->in[I_F1G] + wl, 1024, 2816, (bf16_t*)(ws + WS_WGU1), 5, uu, T, I);
;         else if (mi == 1) conv_tile4(P->in[I_F1U] + wl, 1024, 2816, (bf16_t*)(ws + WS_WGU1), 6, uu, T, I);
;         else if (mi == 2) conv_tile4(P->in[I_F1D] + wl, 2816, 1024, (bf16_t*)(ws + WS_WD1), 0, uu, T, I);
;         else if (mi == 3) conv_tile4(P->in[I_WIN] + wl, 1024, 2816, (bf16_t*)(ws + WS_WIN), 4, uu, T, I);
;         else if (mi == 4) conv_tile4(P->in[I_F2G] + wl, 1024, 2816, (bf16_t*)(ws + WS_WGU2), 5, uu, T, I);
;         else if (mi == 5) conv_tile4(P->in[I_F2U] + wl, 1024, 2816, (bf16_t*)(ws + WS_WGU2), 6, uu, T, I);
;         else if (mi == 6) conv_tile4(P->in[I_F2D] + wl, 2816, 1024, (bf16_t*)(ws + WS_WD2), 0, uu, T, I);
;         else              conv_tile4(P->in[I_WOUT] + (size_t)l * 1024 * 1024, 1024, 1024, (bf16_t*)(ws + WS_WOUT), 0, uu, T, I);
;     }
; __global__ void __launch_bounds__(512) mega(Params Pval) {
;     ...
;             if (I.nb > 144) { if (I.bid < 72) { EpiAda E{(float*)(ws + WS_MOD), P->in[I_BADA]}; run_gemm(lds, (const bf16_t*)(ws + WS_AADA), (const bf16_t*)(ws + WS_R2), 256, 2 * 9216, 1024, E, I); }
;                               else { Ids J = I; J.bid = I.bid - 72; J.nb = I.nb - 72; convert_layer(P, 0, lds, J); } }
.LBB0_654:
	s_and_b64 vcc, exec, s[4:5]
	s_cbranch_vccz .LBB0_716
	s_mov_b64 s[2:3], -1
	s_and_b64 vcc, exec, s[0:1]
	s_cbranch_vccz .LBB0_688
	s_cmpk_gt_i32 s93, 0x557
	s_cbranch_scc1 .LBB0_687
	s_add_i32 s16, s93, 0xffffffb8
	s_add_i32 s17, s72, 0xffffffb8
	s_add_i32 s18, s93, 0xfffffb98
	s_movk_i32 s100, 0x44f
	s_branch .LBB0_659
.LBB0_658:
	s_add_i32 s16, s17, s16
	s_add_i32 s18, s18, s17
	s_cmp_gt_i32 s16, s100
	s_waitcnt lgkmcnt(0)
	s_cbranch_scc1 .LBB0_687

; __device__ __forceinline__ void convert_layer(PP P, int l, LAS unsigned char* lds, const Ids I) {
;     ...
;     for (int u = BID; u < 7 * 176 + 64; u += NB) {
;         const int mi = u / 176, uu = u - mi * 176;
;         if (mi == 0)      conv_tile4(P->in[I_F1G] + wl, 1024, 2816, (bf16_t*)(ws + WS_WGU1), 5, uu, T, I);
;         else if (mi == 1) conv_tile4(P->in[I_F1U] + wl, 1024, 2816, (bf16_t*)(ws + WS_WGU1), 6, uu, T, I);
;         else if (mi == 2) conv_tile4(P->in[I_F1D] + wl, 2816, 1024, (bf16_t*)(ws + WS_WD1), 0, uu, T, I);
;         else if (mi == 3) conv_tile4(P->in[I_WIN] + wl, 1024, 2816, (bf16_t*)(ws + WS_WIN), 4, uu, T, I);
;         else if (mi == 4) conv_tile4(P->in[I_F2G] + wl, 1024, 2816, (bf16_t*)(ws + WS_WGU2), 5, uu, T, I);
;         else if (mi == 5) conv_tile4(P->in[I_F2U] + wl, 1024, 2816, (bf16_t*)(ws + WS_WGU2), 6, uu, T, I);
;         else if (mi == 6) conv_tile4(P->in[I_F2D] + wl, 2816, 1024, (bf16_t*)(ws + WS_WD2), 0, uu, T, I);
;         else              conv_tile4(P->in[I_WOUT] + (size_t)l * 1024 * 1024, 1024, 1024, (bf16_t*)(ws + WS_WOUT), 0, uu, T, I);
;     }
; __global__ void __launch_bounds__(512) mega(Params Pval) {
;     ...
;             if (I.nb > 144) { if (I.bid < 72) { EpiAda E{(float*)(ws + WS_MOD), P->in[I_BADA]}; run_gemm(lds, (const bf16_t*)(ws + WS_AADA), (const bf16_t*)(ws + WS_R2), 256, 2 * 9216, 1024, E, I); }
;                               else { Ids J = I; J.bid = I.bid - 72; J.nb = I.nb - 72; convert_layer(P, 0, lds, J); } }
.LBB0_715:
	s_barrier
	s_add_i32 s16, s93, 0x450
	s_movk_i32 s17, 0x48
	s_add_i32 s18, s93, 48
	s_movk_i32 s100, 0x50f
	s_add_u32 s48, s86, 0x4000
	s_addc_u32 s49, s87, 0
	s_branch .LBB0_659
